# mixer prenorm: rows iterated from last to first so the context rows (partial-sum reduction) are processed first, latent rows form the tail
# speedup vs baseline: 1.0117x; 1.0033x over previous
.LBB0_424:
	s_ashr_i32 s3, s3, 6
	s_add_i32 s12, s3, s40
	s_cmpk_gt_i32 s12, 0x43ff
	v_readlane_b32 s33, v255, 4
	s_cbranch_scc1 .LBB0_442
	v_readlane_b32 s4, v255, 38
	s_add_u32 s4, s0, s4
	s_addc_u32 s5, s1, 0
	s_load_dwordx2 s[14:15], s[4:5], 0x0
	v_lshlrev_b32_e32 v0, 2, v2
	s_load_dwordx2 s[4:5], s[0:1], 0xc8
	s_waitcnt vmcnt(12)
	v_and_b32_e32 v34, 0xfc, v0
	v_lshlrev_b32_e32 v0, 2, v34
	v_and_b32_e32 v3, 64, v228
	v_add_u32_e32 v3, 64, v3
	s_waitcnt lgkmcnt(0)
	v_lshl_add_u64 v[4:5], s[4:5], 0, v[0:1]
	s_mov_b64 s[4:5], 0xbb00000
	v_lshl_add_u64 v[36:37], v[4:5], 0, s[4:5]
	v_xor_b32_e32 v4, 1, v228
	v_cmp_lt_i32_e32 vcc, v4, v3
	v_readlane_b32 s4, v255, 52
	v_readlane_b32 s5, v255, 53
	v_cndmask_b32_e32 v4, v228, v4, vcc
	v_lshlrev_b32_e32 v35, 2, v4
	v_xor_b32_e32 v4, 2, v228
	v_cmp_lt_i32_e32 vcc, v4, v3
	s_ashr_i32 s13, s12, 31
	v_lshl_add_u64 v[44:45], s[4:5], 0, v[0:1]
	v_cndmask_b32_e32 v4, v228, v4, vcc
	s_waitcnt vmcnt(8)
	v_lshlrev_b32_e32 v39, 2, v4
	v_xor_b32_e32 v4, 4, v228
	v_cmp_lt_i32_e32 vcc, v4, v3
	s_lshl_b64 s[4:5], s[12:13], 11
	v_readlane_b32 s8, v255, 54
	v_cndmask_b32_e32 v4, v228, v4, vcc
	v_lshlrev_b32_e32 v41, 2, v4
	v_xor_b32_e32 v4, 8, v228
	v_cmp_lt_i32_e32 vcc, v4, v3
	v_and_b32_e32 v0, 63, v2
	s_add_u32 s4, s8, s4
	v_cndmask_b32_e32 v4, v228, v4, vcc
	v_lshlrev_b32_e32 v43, 2, v4
	v_xor_b32_e32 v4, 16, v228
	v_cmp_lt_i32_e32 vcc, v4, v3
	v_readlane_b32 s8, v255, 55
	v_lshlrev_b32_e32 v0, 3, v0
	v_cndmask_b32_e32 v4, v228, v4, vcc
	s_addc_u32 s5, s8, s5
	v_lshlrev_b32_e32 v52, 2, v4
	v_xor_b32_e32 v4, 32, v228
	s_waitcnt vmcnt(4)
	v_lshl_add_u64 v[46:47], s[4:5], 0, v[0:1]
	v_readlane_b32 s4, v254, 47
	v_cmp_lt_i32_e32 vcc, v4, v3
	s_add_i32 s3, s4, s3
	s_lshl_b32 s3, s3, 10
	v_cndmask_b32_e32 v3, v228, v4, vcc
	v_or_b32_e32 v38, 0x100, v34
	v_or_b32_e32 v40, 0x200, v34
	v_or_b32_e32 v42, 0x300, v34
	v_lshlrev_b32_e32 v53, 2, v3
	s_add_i32 s4, s3, 0xff000000
	s_mov_b64 s[16:17], 0
	v_lshlrev_b32_e32 v0, 2, v34
	s_mov_b32 s3, s12
	s_sub_i32 s8, 0x43ff, s12
	s_lshr_b32 s8, s8, 12
	s_mul_i32 s9, s8, s30
	s_add_i32 s3, s3, s9
	s_mov_b32 s16, s9
	s_mul_hi_u32 s17, s8, s30
	s_mul_i32 s9, s8, s33
	s_add_i32 s4, s4, s9
	v_readlane_b32 s20, v254, 60
	v_readlane_b32 s21, v254, 61
	s_nop 0
	s_mul_i32 s9, s8, s21
	s_mul_hi_u32 s21, s8, s20
	s_add_i32 s21, s21, s9
	s_mul_i32 s20, s8, s20
	s_nop 0
	v_lshl_add_u64 v[46:47], v[46:47], 0, s[20:21]
	s_branch .LBB0_427
.LBB0_426:
	s_sub_i32 s3, s3, s30
	s_sub_u32 s16, s16, s30
	v_readlane_b32 s8, v254, 60
	s_subb_u32 s17, s17, s31
	s_sub_i32 s4, s4, s33
	v_readlane_b32 s9, v254, 61
	s_nop 0
	s_sub_u32 s8, 0, s8
	s_subb_u32 s9, 0, s9
	s_cmp_lt_i32 s3, 0
	s_nop 0
	v_lshl_add_u64 v[46:47], v[46:47], 0, s[8:9]
	s_cbranch_scc1 .LBB0_442
